# GEMM tile loops: dropped the vmcnt(0) in the accumulator zero-init (it only waited for the previous tile's epilogue stores)
# baseline (speedup 1.0000x reference)
.LBB0_218:
	s_lshl_b32 s16, s42, 8
	s_ashr_i32 s17, s16, 31
	s_lshl_b64 s[16:17], s[16:17], 11
	s_add_u32 s16, s80, s16
	s_addc_u32 s17, s81, s17
	s_and_b64 s[22:23], s[2:3], exec
	s_cselect_b32 s44, s17, s27
	s_cselect_b32 s45, s16, s26
	s_lshl_b32 s22, s41, 8
	s_ashr_i32 s23, s22, 31
	s_lshl_b64 s[22:23], s[22:23], 11
	s_add_u32 s22, s29, s22
	s_addc_u32 s23, s30, s23
	s_and_b64 s[24:25], s[2:3], exec
	s_cselect_b32 s46, s23, s5
	s_cselect_b32 s47, s22, s4
	s_add_u32 s48, s4, 0x100
	s_addc_u32 s49, s5, 0
	s_add_u32 s4, s26, 0x40080
	v_mov_b32_e32 v2, 0
	s_addc_u32 s5, s27, 0
	s_mov_b32 s50, -2
	v_mov_b32_e32 v3, v2
	v_mov_b32_e32 v4, v2
	v_mov_b32_e32 v5, v2
	v_mov_b32_e32 v6, v2
	v_mov_b32_e32 v7, v2
	v_mov_b32_e32 v8, v2
	v_mov_b32_e32 v9, v2
	v_mov_b32_e32 v18, v2
	v_mov_b32_e32 v19, v2
	v_mov_b32_e32 v20, v2
	v_mov_b32_e32 v21, v2
	v_mov_b32_e32 v22, v2
	v_mov_b32_e32 v23, v2
	v_mov_b32_e32 v24, v2
	v_mov_b32_e32 v25, v2
	v_mov_b32_e32 v34, v2
	v_mov_b32_e32 v35, v2
	v_mov_b32_e32 v36, v2
	v_mov_b32_e32 v37, v2
	v_mov_b32_e32 v38, v2
	v_mov_b32_e32 v39, v2
	v_mov_b32_e32 v40, v2
	v_mov_b32_e32 v41, v2
	v_mov_b32_e32 v50, v2
	v_mov_b32_e32 v51, v2
	v_mov_b32_e32 v52, v2
	v_mov_b32_e32 v53, v2
	v_mov_b32_e32 v54, v2
	v_mov_b32_e32 v55, v2
	v_mov_b32_e32 v56, v2
	v_mov_b32_e32 v57, v2
	v_mov_b32_e32 v10, v2
	v_mov_b32_e32 v11, v2
	v_mov_b32_e32 v12, v2
	v_mov_b32_e32 v13, v2
	v_mov_b32_e32 v14, v2
	v_mov_b32_e32 v15, v2
	v_mov_b32_e32 v16, v2
	v_mov_b32_e32 v17, v2
	v_mov_b32_e32 v26, v2
	v_mov_b32_e32 v27, v2
	v_mov_b32_e32 v28, v2
	v_mov_b32_e32 v29, v2
	v_mov_b32_e32 v30, v2
	v_mov_b32_e32 v31, v2
	v_mov_b32_e32 v32, v2
	v_mov_b32_e32 v33, v2
	v_mov_b32_e32 v42, v2
	v_mov_b32_e32 v43, v2
	v_mov_b32_e32 v44, v2
	v_mov_b32_e32 v45, v2
	v_mov_b32_e32 v46, v2
	v_mov_b32_e32 v47, v2
	v_mov_b32_e32 v48, v2
	v_mov_b32_e32 v49, v2
	v_mov_b32_e32 v58, v2
	v_mov_b32_e32 v59, v2
	v_mov_b32_e32 v60, v2
	v_mov_b32_e32 v61, v2
	v_mov_b32_e32 v62, v2
	v_mov_b32_e32 v63, v2
	v_mov_b32_e32 v64, v2
	v_mov_b32_e32 v65, v2
	v_mov_b32_e32 v66, v2
	v_mov_b32_e32 v67, v2
	v_mov_b32_e32 v68, v2
	v_mov_b32_e32 v69, v2
	v_mov_b32_e32 v70, v2
	v_mov_b32_e32 v71, v2
	v_mov_b32_e32 v72, v2
	v_mov_b32_e32 v73, v2
	v_mov_b32_e32 v82, v2
	v_mov_b32_e32 v83, v2
	v_mov_b32_e32 v84, v2
	v_mov_b32_e32 v85, v2
	v_mov_b32_e32 v86, v2
	v_mov_b32_e32 v87, v2
	v_mov_b32_e32 v88, v2
	v_mov_b32_e32 v89, v2
	v_mov_b32_e32 v98, v2
	v_mov_b32_e32 v99, v2
	v_mov_b32_e32 v100, v2
	v_mov_b32_e32 v101, v2
	v_mov_b32_e32 v102, v2
	v_mov_b32_e32 v103, v2
	v_mov_b32_e32 v104, v2
	v_mov_b32_e32 v105, v2
	v_mov_b32_e32 v114, v2
	v_mov_b32_e32 v115, v2
	v_mov_b32_e32 v116, v2
	v_mov_b32_e32 v117, v2
	v_mov_b32_e32 v118, v2
	v_mov_b32_e32 v119, v2
	v_mov_b32_e32 v120, v2
	v_mov_b32_e32 v121, v2
	v_mov_b32_e32 v74, v2
	v_mov_b32_e32 v75, v2
	v_mov_b32_e32 v76, v2
	v_mov_b32_e32 v77, v2
	v_mov_b32_e32 v78, v2
	v_mov_b32_e32 v79, v2
	v_mov_b32_e32 v80, v2
	v_mov_b32_e32 v81, v2
	v_mov_b32_e32 v90, v2
	v_mov_b32_e32 v91, v2
	v_mov_b32_e32 v92, v2
	v_mov_b32_e32 v93, v2
	v_mov_b32_e32 v94, v2
	v_mov_b32_e32 v95, v2
	v_mov_b32_e32 v96, v2
	v_mov_b32_e32 v97, v2
	v_mov_b32_e32 v106, v2
	v_mov_b32_e32 v107, v2
	v_mov_b32_e32 v108, v2
	v_mov_b32_e32 v109, v2
	v_mov_b32_e32 v110, v2
	v_mov_b32_e32 v111, v2
	v_mov_b32_e32 v112, v2
	v_mov_b32_e32 v113, v2
	v_mov_b32_e32 v122, v2
	v_mov_b32_e32 v123, v2
	v_mov_b32_e32 v124, v2
	v_mov_b32_e32 v125, v2
	v_mov_b32_e32 v126, v2
	v_mov_b32_e32 v127, v2
	v_mov_b32_e32 v128, v2
	v_mov_b32_e32 v129, v2

.LBB0_323:
	s_add_u32 s49, s26, 0x100
	v_mov_b32_e32 v2, 0
	s_addc_u32 s50, s27, 0
	s_mov_b32 s51, -2
	v_mov_b32_e32 v3, v2
	v_mov_b32_e32 v4, v2
	v_mov_b32_e32 v5, v2
	v_mov_b32_e32 v6, v2
	v_mov_b32_e32 v7, v2
	v_mov_b32_e32 v8, v2
	v_mov_b32_e32 v9, v2
	v_mov_b32_e32 v18, v2
	v_mov_b32_e32 v19, v2
	v_mov_b32_e32 v20, v2
	v_mov_b32_e32 v21, v2
	v_mov_b32_e32 v22, v2
	v_mov_b32_e32 v23, v2
	v_mov_b32_e32 v24, v2
	v_mov_b32_e32 v25, v2
	v_mov_b32_e32 v34, v2
	v_mov_b32_e32 v35, v2
	v_mov_b32_e32 v36, v2
	v_mov_b32_e32 v37, v2
	v_mov_b32_e32 v38, v2
	v_mov_b32_e32 v39, v2
	v_mov_b32_e32 v40, v2
	v_mov_b32_e32 v41, v2
	v_mov_b32_e32 v50, v2
	v_mov_b32_e32 v51, v2
	v_mov_b32_e32 v52, v2
	v_mov_b32_e32 v53, v2
	v_mov_b32_e32 v54, v2
	v_mov_b32_e32 v55, v2
	v_mov_b32_e32 v56, v2
	v_mov_b32_e32 v57, v2
	v_mov_b32_e32 v10, v2
	v_mov_b32_e32 v11, v2
	v_mov_b32_e32 v12, v2
	v_mov_b32_e32 v13, v2
	v_mov_b32_e32 v14, v2
	v_mov_b32_e32 v15, v2
	v_mov_b32_e32 v16, v2
	v_mov_b32_e32 v17, v2
	v_mov_b32_e32 v26, v2
	v_mov_b32_e32 v27, v2
	v_mov_b32_e32 v28, v2
	v_mov_b32_e32 v29, v2
	v_mov_b32_e32 v30, v2
	v_mov_b32_e32 v31, v2
	v_mov_b32_e32 v32, v2
	v_mov_b32_e32 v33, v2
	v_mov_b32_e32 v42, v2
	v_mov_b32_e32 v43, v2
	v_mov_b32_e32 v44, v2
	v_mov_b32_e32 v45, v2
	v_mov_b32_e32 v46, v2
	v_mov_b32_e32 v47, v2
	v_mov_b32_e32 v48, v2
	v_mov_b32_e32 v49, v2
	v_mov_b32_e32 v58, v2
	v_mov_b32_e32 v59, v2
	v_mov_b32_e32 v60, v2
	v_mov_b32_e32 v61, v2
	v_mov_b32_e32 v62, v2
	v_mov_b32_e32 v63, v2
	v_mov_b32_e32 v64, v2
	v_mov_b32_e32 v65, v2
	v_mov_b32_e32 v66, v2
	v_mov_b32_e32 v67, v2
	v_mov_b32_e32 v68, v2
	v_mov_b32_e32 v69, v2
	v_mov_b32_e32 v70, v2
	v_mov_b32_e32 v71, v2
	v_mov_b32_e32 v72, v2
	v_mov_b32_e32 v73, v2
	v_mov_b32_e32 v82, v2
	v_mov_b32_e32 v83, v2
	v_mov_b32_e32 v84, v2
	v_mov_b32_e32 v85, v2
	v_mov_b32_e32 v86, v2
	v_mov_b32_e32 v87, v2
	v_mov_b32_e32 v88, v2
	v_mov_b32_e32 v89, v2
	v_mov_b32_e32 v98, v2
	v_mov_b32_e32 v99, v2
	v_mov_b32_e32 v100, v2
	v_mov_b32_e32 v101, v2
	v_mov_b32_e32 v102, v2
	v_mov_b32_e32 v103, v2
	v_mov_b32_e32 v104, v2
	v_mov_b32_e32 v105, v2
	v_mov_b32_e32 v114, v2
	v_mov_b32_e32 v115, v2
	v_mov_b32_e32 v116, v2
	v_mov_b32_e32 v117, v2
	v_mov_b32_e32 v118, v2
	v_mov_b32_e32 v119, v2
	v_mov_b32_e32 v120, v2
	v_mov_b32_e32 v121, v2
	v_mov_b32_e32 v74, v2
	v_mov_b32_e32 v75, v2
	v_mov_b32_e32 v76, v2
	v_mov_b32_e32 v77, v2
	v_mov_b32_e32 v78, v2
	v_mov_b32_e32 v79, v2
	v_mov_b32_e32 v80, v2
	v_mov_b32_e32 v81, v2
	v_mov_b32_e32 v90, v2
	v_mov_b32_e32 v91, v2
	v_mov_b32_e32 v92, v2
	v_mov_b32_e32 v93, v2
	v_mov_b32_e32 v94, v2
	v_mov_b32_e32 v95, v2
	v_mov_b32_e32 v96, v2
	v_mov_b32_e32 v97, v2
	v_mov_b32_e32 v106, v2
	v_mov_b32_e32 v107, v2
	v_mov_b32_e32 v108, v2
	v_mov_b32_e32 v109, v2
	v_mov_b32_e32 v110, v2
	v_mov_b32_e32 v111, v2
	v_mov_b32_e32 v112, v2
	v_mov_b32_e32 v113, v2
	v_mov_b32_e32 v122, v2
	v_mov_b32_e32 v123, v2
	v_mov_b32_e32 v124, v2
	v_mov_b32_e32 v125, v2
	v_mov_b32_e32 v126, v2
	v_mov_b32_e32 v127, v2
	v_mov_b32_e32 v128, v2
	v_mov_b32_e32 v129, v2

.LBB0_360:
	s_lshl_b32 s10, s35, 8
	s_ashr_i32 s11, s10, 31
	s_lshl_b64 s[10:11], s[10:11], 11
	s_add_u32 s10, s80, s10
	s_addc_u32 s11, s81, s11
	s_and_b64 s[12:13], s[2:3], exec
	s_cselect_b32 s38, s11, s17
	s_cselect_b32 s39, s10, s16
	s_lshl_b32 s12, s34, 8
	s_ashr_i32 s13, s12, 31
	s_lshl_b64 s[12:13], s[12:13], 11
	s_add_u32 s12, s22, s12
	s_addc_u32 s13, s23, s13
	s_and_b64 s[20:21], s[2:3], exec
	s_cselect_b32 s40, s13, s15
	s_cselect_b32 s41, s12, s14
	s_add_u32 s42, s14, 0x100
	s_addc_u32 s43, s15, 0
	s_add_u32 s14, s16, 0x40080
	v_mov_b32_e32 v2, 0
	s_addc_u32 s15, s17, 0
	s_mov_b32 s44, -2
	v_mov_b32_e32 v3, v2
	v_mov_b32_e32 v4, v2
	v_mov_b32_e32 v5, v2
	v_mov_b32_e32 v6, v2
	v_mov_b32_e32 v7, v2
	v_mov_b32_e32 v8, v2
	v_mov_b32_e32 v9, v2
	v_mov_b32_e32 v18, v2
	v_mov_b32_e32 v19, v2
	v_mov_b32_e32 v20, v2
	v_mov_b32_e32 v21, v2
	v_mov_b32_e32 v22, v2
	v_mov_b32_e32 v23, v2
	v_mov_b32_e32 v24, v2
	v_mov_b32_e32 v25, v2
	v_mov_b32_e32 v34, v2
	v_mov_b32_e32 v35, v2
	v_mov_b32_e32 v36, v2
	v_mov_b32_e32 v37, v2
	v_mov_b32_e32 v38, v2
	v_mov_b32_e32 v39, v2
	v_mov_b32_e32 v40, v2
	v_mov_b32_e32 v41, v2
	v_mov_b32_e32 v50, v2
	v_mov_b32_e32 v51, v2
	v_mov_b32_e32 v52, v2
	v_mov_b32_e32 v53, v2
	v_mov_b32_e32 v54, v2
	v_mov_b32_e32 v55, v2
	v_mov_b32_e32 v56, v2
	v_mov_b32_e32 v57, v2
	v_mov_b32_e32 v10, v2
	v_mov_b32_e32 v11, v2
	v_mov_b32_e32 v12, v2
	v_mov_b32_e32 v13, v2
	v_mov_b32_e32 v14, v2
	v_mov_b32_e32 v15, v2
	v_mov_b32_e32 v16, v2
	v_mov_b32_e32 v17, v2
	v_mov_b32_e32 v26, v2
	v_mov_b32_e32 v27, v2
	v_mov_b32_e32 v28, v2
	v_mov_b32_e32 v29, v2
	v_mov_b32_e32 v30, v2
	v_mov_b32_e32 v31, v2
	v_mov_b32_e32 v32, v2
	v_mov_b32_e32 v33, v2
	v_mov_b32_e32 v42, v2
	v_mov_b32_e32 v43, v2
	v_mov_b32_e32 v44, v2
	v_mov_b32_e32 v45, v2
	v_mov_b32_e32 v46, v2
	v_mov_b32_e32 v47, v2
	v_mov_b32_e32 v48, v2
	v_mov_b32_e32 v49, v2
	v_mov_b32_e32 v58, v2
	v_mov_b32_e32 v59, v2
	v_mov_b32_e32 v60, v2
	v_mov_b32_e32 v61, v2
	v_mov_b32_e32 v62, v2
	v_mov_b32_e32 v63, v2
	v_mov_b32_e32 v64, v2
	v_mov_b32_e32 v65, v2
	v_mov_b32_e32 v66, v2
	v_mov_b32_e32 v67, v2
	v_mov_b32_e32 v68, v2
	v_mov_b32_e32 v69, v2
	v_mov_b32_e32 v70, v2
	v_mov_b32_e32 v71, v2
	v_mov_b32_e32 v72, v2
	v_mov_b32_e32 v73, v2
	v_mov_b32_e32 v82, v2
	v_mov_b32_e32 v83, v2
	v_mov_b32_e32 v84, v2
	v_mov_b32_e32 v85, v2
	v_mov_b32_e32 v86, v2
	v_mov_b32_e32 v87, v2
	v_mov_b32_e32 v88, v2
	v_mov_b32_e32 v89, v2
	v_mov_b32_e32 v98, v2
	v_mov_b32_e32 v99, v2
	v_mov_b32_e32 v100, v2
	v_mov_b32_e32 v101, v2
	v_mov_b32_e32 v102, v2
	v_mov_b32_e32 v103, v2
	v_mov_b32_e32 v104, v2
	v_mov_b32_e32 v105, v2
	v_mov_b32_e32 v114, v2
	v_mov_b32_e32 v115, v2
	v_mov_b32_e32 v116, v2
	v_mov_b32_e32 v117, v2
	v_mov_b32_e32 v118, v2
	v_mov_b32_e32 v119, v2
	v_mov_b32_e32 v120, v2
	v_mov_b32_e32 v121, v2
	v_mov_b32_e32 v74, v2
	v_mov_b32_e32 v75, v2
	v_mov_b32_e32 v76, v2
	v_mov_b32_e32 v77, v2
	v_mov_b32_e32 v78, v2
	v_mov_b32_e32 v79, v2
	v_mov_b32_e32 v80, v2
	v_mov_b32_e32 v81, v2
	v_mov_b32_e32 v90, v2
	v_mov_b32_e32 v91, v2
	v_mov_b32_e32 v92, v2
	v_mov_b32_e32 v93, v2
	v_mov_b32_e32 v94, v2
	v_mov_b32_e32 v95, v2
	v_mov_b32_e32 v96, v2
	v_mov_b32_e32 v97, v2
	v_mov_b32_e32 v106, v2
	v_mov_b32_e32 v107, v2
	v_mov_b32_e32 v108, v2
	v_mov_b32_e32 v109, v2
	v_mov_b32_e32 v110, v2
	v_mov_b32_e32 v111, v2
	v_mov_b32_e32 v112, v2
	v_mov_b32_e32 v113, v2
	v_mov_b32_e32 v122, v2
	v_mov_b32_e32 v123, v2
	v_mov_b32_e32 v124, v2
	v_mov_b32_e32 v125, v2
	v_mov_b32_e32 v126, v2
	v_mov_b32_e32 v127, v2
	v_mov_b32_e32 v128, v2
	v_mov_b32_e32 v129, v2

.LBB0_391:
	s_lshl_b32 s20, s42, 8
	s_ashr_i32 s21, s20, 31
	s_lshl_b64 s[20:21], s[20:21], 11
	s_add_u32 s20, s18, s20
	s_addc_u32 s21, s19, s21
	s_and_b64 s[22:23], s[4:5], exec
	s_cselect_b32 s45, s21, s25
	s_cselect_b32 s46, s20, s24
	s_lshl_b32 s22, s41, 8
	s_ashr_i32 s23, s22, 31
	s_lshl_b64 s[22:23], s[22:23], 11
	s_add_u32 s22, s29, s22
	s_addc_u32 s23, s30, s23
	s_and_b64 s[26:27], s[4:5], exec
	s_cselect_b32 s47, s23, s7
	s_cselect_b32 s48, s22, s6
	s_add_u32 s49, s6, 0x100
	s_addc_u32 s50, s7, 0
	s_add_u32 s6, s24, 0x40080
	v_mov_b32_e32 v2, 0
	s_addc_u32 s7, s25, 0
	s_mov_b32 s51, -2
	v_mov_b32_e32 v3, v2
	v_mov_b32_e32 v4, v2
	v_mov_b32_e32 v5, v2
	v_mov_b32_e32 v6, v2
	v_mov_b32_e32 v7, v2
	v_mov_b32_e32 v8, v2
	v_mov_b32_e32 v9, v2
	v_mov_b32_e32 v18, v2
	v_mov_b32_e32 v19, v2
	v_mov_b32_e32 v20, v2
	v_mov_b32_e32 v21, v2
	v_mov_b32_e32 v22, v2
	v_mov_b32_e32 v23, v2
	v_mov_b32_e32 v24, v2
	v_mov_b32_e32 v25, v2
	v_mov_b32_e32 v34, v2
	v_mov_b32_e32 v35, v2
	v_mov_b32_e32 v36, v2
	v_mov_b32_e32 v37, v2
	v_mov_b32_e32 v38, v2
	v_mov_b32_e32 v39, v2
	v_mov_b32_e32 v40, v2
	v_mov_b32_e32 v41, v2
	v_mov_b32_e32 v50, v2
	v_mov_b32_e32 v51, v2
	v_mov_b32_e32 v52, v2
	v_mov_b32_e32 v53, v2
	v_mov_b32_e32 v54, v2
	v_mov_b32_e32 v55, v2
	v_mov_b32_e32 v56, v2
	v_mov_b32_e32 v57, v2
	v_mov_b32_e32 v10, v2
	v_mov_b32_e32 v11, v2
	v_mov_b32_e32 v12, v2
	v_mov_b32_e32 v13, v2
	v_mov_b32_e32 v14, v2
	v_mov_b32_e32 v15, v2
	v_mov_b32_e32 v16, v2
	v_mov_b32_e32 v17, v2
	v_mov_b32_e32 v26, v2
	v_mov_b32_e32 v27, v2
	v_mov_b32_e32 v28, v2
	v_mov_b32_e32 v29, v2
	v_mov_b32_e32 v30, v2
	v_mov_b32_e32 v31, v2
	v_mov_b32_e32 v32, v2
	v_mov_b32_e32 v33, v2
	v_mov_b32_e32 v42, v2
	v_mov_b32_e32 v43, v2
	v_mov_b32_e32 v44, v2
	v_mov_b32_e32 v45, v2
	v_mov_b32_e32 v46, v2
	v_mov_b32_e32 v47, v2
	v_mov_b32_e32 v48, v2
	v_mov_b32_e32 v49, v2
	v_mov_b32_e32 v58, v2
	v_mov_b32_e32 v59, v2
	v_mov_b32_e32 v60, v2
	v_mov_b32_e32 v61, v2
	v_mov_b32_e32 v62, v2
	v_mov_b32_e32 v63, v2
	v_mov_b32_e32 v64, v2
	v_mov_b32_e32 v65, v2
	v_mov_b32_e32 v66, v2
	v_mov_b32_e32 v67, v2
	v_mov_b32_e32 v68, v2
	v_mov_b32_e32 v69, v2
	v_mov_b32_e32 v70, v2
	v_mov_b32_e32 v71, v2
	v_mov_b32_e32 v72, v2
	v_mov_b32_e32 v73, v2
	v_mov_b32_e32 v82, v2
	v_mov_b32_e32 v83, v2
	v_mov_b32_e32 v84, v2
	v_mov_b32_e32 v85, v2
	v_mov_b32_e32 v86, v2
	v_mov_b32_e32 v87, v2
	v_mov_b32_e32 v88, v2
	v_mov_b32_e32 v89, v2
	v_mov_b32_e32 v98, v2
	v_mov_b32_e32 v99, v2
	v_mov_b32_e32 v100, v2
	v_mov_b32_e32 v101, v2
	v_mov_b32_e32 v102, v2
	v_mov_b32_e32 v103, v2
	v_mov_b32_e32 v104, v2
	v_mov_b32_e32 v105, v2
	v_mov_b32_e32 v114, v2
	v_mov_b32_e32 v115, v2
	v_mov_b32_e32 v116, v2
	v_mov_b32_e32 v117, v2
	v_mov_b32_e32 v118, v2
	v_mov_b32_e32 v119, v2
	v_mov_b32_e32 v120, v2
	v_mov_b32_e32 v121, v2
	v_mov_b32_e32 v74, v2
	v_mov_b32_e32 v75, v2
	v_mov_b32_e32 v76, v2
	v_mov_b32_e32 v77, v2
	v_mov_b32_e32 v78, v2
	v_mov_b32_e32 v79, v2
	v_mov_b32_e32 v80, v2
	v_mov_b32_e32 v81, v2
	v_mov_b32_e32 v90, v2
	v_mov_b32_e32 v91, v2
	v_mov_b32_e32 v92, v2
	v_mov_b32_e32 v93, v2
	v_mov_b32_e32 v94, v2
	v_mov_b32_e32 v95, v2
	v_mov_b32_e32 v96, v2
	v_mov_b32_e32 v97, v2
	v_mov_b32_e32 v106, v2
	v_mov_b32_e32 v107, v2
	v_mov_b32_e32 v108, v2
	v_mov_b32_e32 v109, v2
	v_mov_b32_e32 v110, v2
	v_mov_b32_e32 v111, v2
	v_mov_b32_e32 v112, v2
	v_mov_b32_e32 v113, v2
	v_mov_b32_e32 v122, v2
	v_mov_b32_e32 v123, v2
	v_mov_b32_e32 v124, v2
	v_mov_b32_e32 v125, v2
	v_mov_b32_e32 v126, v2
	v_mov_b32_e32 v127, v2
	v_mov_b32_e32 v128, v2
	v_mov_b32_e32 v129, v2

.LBB0_511:
	s_lshl_b32 s22, s50, 8
	s_ashr_i32 s23, s22, 31
	s_lshl_b64 s[22:23], s[22:23], 11
	s_add_u32 s22, s31, s22
	s_addc_u32 s23, s34, s23
	s_and_b64 s[6:7], s[6:7], exec
	s_cselect_b32 s53, s23, s27
	s_cselect_b32 s54, s22, s26
	s_add_u32 s55, s26, 0x100
	s_addc_u32 s56, s27, 0
	s_add_u32 s6, s24, 0x80
	s_addc_u32 s7, s25, 0
	v_mov_b32_e32 v2, 0
	v_lshl_add_u64 v[38:39], s[6:7], 0, v[172:173]
	v_lshl_add_u64 v[40:41], s[6:7], 0, v[174:175]
	s_mov_b32 s57, -2
	s_mov_b64 s[6:7], 0
	v_mov_b32_e32 v3, v2
	v_mov_b32_e32 v4, v2
	v_mov_b32_e32 v5, v2
	v_mov_b32_e32 v6, v2
	v_mov_b32_e32 v7, v2
	v_mov_b32_e32 v8, v2
	v_mov_b32_e32 v9, v2
	v_mov_b32_e32 v18, v2
	v_mov_b32_e32 v19, v2
	v_mov_b32_e32 v20, v2
	v_mov_b32_e32 v21, v2
	v_mov_b32_e32 v22, v2
	v_mov_b32_e32 v23, v2
	s_waitcnt lgkmcnt(0)
	v_mov_b32_e32 v24, v2
	v_mov_b32_e32 v25, v2
	v_mov_b32_e32 v34, v2
	v_mov_b32_e32 v35, v2
	v_mov_b32_e32 v36, v2
	v_mov_b32_e32 v37, v2
	v_mov_b32_e32 v46, v2
	v_mov_b32_e32 v47, v2
	v_mov_b32_e32 v48, v2
	v_mov_b32_e32 v49, v2
	v_mov_b32_e32 v74, v2
	v_mov_b32_e32 v75, v2
	v_mov_b32_e32 v76, v2
	v_mov_b32_e32 v77, v2
	v_mov_b32_e32 v86, v2
	v_mov_b32_e32 v87, v2
	v_mov_b32_e32 v88, v2
	v_mov_b32_e32 v89, v2
	v_mov_b32_e32 v10, v2
	v_mov_b32_e32 v11, v2
	v_mov_b32_e32 v12, v2
	v_mov_b32_e32 v13, v2
	v_mov_b32_e32 v14, v2
	v_mov_b32_e32 v15, v2
	v_mov_b32_e32 v16, v2
	v_mov_b32_e32 v17, v2
	v_mov_b32_e32 v26, v2
	v_mov_b32_e32 v27, v2
	v_mov_b32_e32 v28, v2
	v_mov_b32_e32 v29, v2
	v_mov_b32_e32 v30, v2
	v_mov_b32_e32 v31, v2
	v_mov_b32_e32 v32, v2
	v_mov_b32_e32 v33, v2
	v_mov_b32_e32 v58, v2
	v_mov_b32_e32 v59, v2
	v_mov_b32_e32 v60, v2
	v_mov_b32_e32 v61, v2
	v_mov_b32_e32 v62, v2
	v_mov_b32_e32 v63, v2
	v_mov_b32_e32 v64, v2
	v_mov_b32_e32 v65, v2
	v_mov_b32_e32 v90, v2
	v_mov_b32_e32 v91, v2
	v_mov_b32_e32 v92, v2
	v_mov_b32_e32 v93, v2
	v_mov_b32_e32 v94, v2
	v_mov_b32_e32 v95, v2
	v_mov_b32_e32 v96, v2
	v_mov_b32_e32 v97, v2
	v_mov_b32_e32 v98, v2
	v_mov_b32_e32 v99, v2
	v_mov_b32_e32 v100, v2
	v_mov_b32_e32 v101, v2
	v_mov_b32_e32 v102, v2
	v_mov_b32_e32 v103, v2
	v_mov_b32_e32 v104, v2
	v_mov_b32_e32 v105, v2
	v_mov_b32_e32 v114, v2
	v_mov_b32_e32 v115, v2
	v_mov_b32_e32 v116, v2
	v_mov_b32_e32 v117, v2
	v_mov_b32_e32 v118, v2
	v_mov_b32_e32 v119, v2
	v_mov_b32_e32 v120, v2
	v_mov_b32_e32 v121, v2
	v_mov_b32_e32 v130, v2
	v_mov_b32_e32 v131, v2
	v_mov_b32_e32 v132, v2
	v_mov_b32_e32 v133, v2
	v_mov_b32_e32 v134, v2
	v_mov_b32_e32 v135, v2
	v_mov_b32_e32 v136, v2
	v_mov_b32_e32 v137, v2
	v_mov_b32_e32 v146, v2
	v_mov_b32_e32 v147, v2
	v_mov_b32_e32 v148, v2
	v_mov_b32_e32 v149, v2
	v_mov_b32_e32 v150, v2
	v_mov_b32_e32 v151, v2
	v_mov_b32_e32 v152, v2
	v_mov_b32_e32 v153, v2
	v_mov_b32_e32 v106, v2
	v_mov_b32_e32 v107, v2
	v_mov_b32_e32 v108, v2
	v_mov_b32_e32 v109, v2
	v_mov_b32_e32 v110, v2
	v_mov_b32_e32 v111, v2
	v_mov_b32_e32 v112, v2
	v_mov_b32_e32 v113, v2
	v_mov_b32_e32 v122, v2
	v_mov_b32_e32 v123, v2
	v_mov_b32_e32 v124, v2
	v_mov_b32_e32 v125, v2
	v_mov_b32_e32 v126, v2
	v_mov_b32_e32 v127, v2
	v_mov_b32_e32 v128, v2
	v_mov_b32_e32 v129, v2
	v_mov_b32_e32 v138, v2
	v_mov_b32_e32 v139, v2
	v_mov_b32_e32 v140, v2
	v_mov_b32_e32 v141, v2
	v_mov_b32_e32 v142, v2
	v_mov_b32_e32 v143, v2
	v_mov_b32_e32 v144, v2
	v_mov_b32_e32 v145, v2
	v_mov_b32_e32 v154, v2
	v_mov_b32_e32 v155, v2
	v_mov_b32_e32 v156, v2
	v_mov_b32_e32 v157, v2
	v_mov_b32_e32 v158, v2
	v_mov_b32_e32 v159, v2
	v_mov_b32_e32 v160, v2
	v_mov_b32_e32 v161, v2
